# P4: GLU K-loop prefetches its GS epilogue lines into L2; attention-combine loop touches next iteration's inputs one iteration ahead (dummy dword loads), waits recounted; on top of v35
# speedup vs baseline: 1.0013x; 1.0013x over previous
.LBB0_1152:
	s_ashr_i32 s23, s22, 31
	s_lshl_b64 s[24:25], s[22:23], 18
	s_add_u32 s24, s8, s24
	s_addc_u32 s25, s9, s25
	s_and_b64 s[26:27], s[0:1], exec
	s_cselect_b32 s23, s25, s35
	s_cselect_b32 s33, s24, s34
	s_ashr_i32 s21, s20, 31
	s_lshl_b64 s[26:27], s[20:21], 18
	s_add_u32 s26, s44, s26
	s_addc_u32 s27, s45, s27
	s_and_b64 s[36:37], s[0:1], exec
	s_cselect_b32 s21, s27, s5
	s_cselect_b32 s54, s26, s4
	s_add_u32 s34, s34, 0x20080
	s_addc_u32 s35, s35, 0
	s_add_u32 s55, s4, 0x100
	v_mov_b32_e32 v2, 0
	s_addc_u32 s56, s5, 0
	s_mov_b32 s57, -2
	s_lshl_b32 s98, s28, 18
	s_lshl_b32 s99, s30, 9
	s_add_u32 s98, s98, s99
	s_add_u32 s98, s6, s98
	s_addc_u32 s99, s7, 0
	v_bfe_u32 v255, v167, 3, 2
	v_and_b32_e32 v254, 0xffffffe0, v167
	v_and_b32_e32 v253, 1, v255
	v_lshl_add_u32 v254, v253, 7, v254
	v_lshlrev_b32_e32 v254, 1, v254
	v_lshrrev_b32_e32 v253, 1, v255
	v_lshl_add_u32 v253, v253, 4, v1
	v_lshl_add_u32 v254, v253, 10, v254
	v_mov_b32_e32 v3, v2
	v_mov_b32_e32 v4, v2
	v_mov_b32_e32 v5, v2
	v_mov_b32_e32 v6, v2
	v_mov_b32_e32 v7, v2
	v_mov_b32_e32 v8, v2
	v_mov_b32_e32 v9, v2
	v_mov_b32_e32 v18, v2
	v_mov_b32_e32 v19, v2
	v_mov_b32_e32 v20, v2
	v_mov_b32_e32 v21, v2
	v_mov_b32_e32 v22, v2
	v_mov_b32_e32 v23, v2
	v_mov_b32_e32 v24, v2
	v_mov_b32_e32 v25, v2
	v_mov_b32_e32 v34, v2
	v_mov_b32_e32 v35, v2
	v_mov_b32_e32 v36, v2
	v_mov_b32_e32 v37, v2
	v_mov_b32_e32 v38, v2
	v_mov_b32_e32 v39, v2
	v_mov_b32_e32 v40, v2
	v_mov_b32_e32 v41, v2
	v_mov_b32_e32 v58, v2
	v_mov_b32_e32 v59, v2
	v_mov_b32_e32 v60, v2
	v_mov_b32_e32 v61, v2
	v_mov_b32_e32 v62, v2
	v_mov_b32_e32 v63, v2
	v_mov_b32_e32 v64, v2
	v_mov_b32_e32 v65, v2
	v_mov_b32_e32 v10, v2
	v_mov_b32_e32 v11, v2
	v_mov_b32_e32 v12, v2
	v_mov_b32_e32 v13, v2
	v_mov_b32_e32 v14, v2
	v_mov_b32_e32 v15, v2
	v_mov_b32_e32 v16, v2
	v_mov_b32_e32 v17, v2
	v_mov_b32_e32 v26, v2
	v_mov_b32_e32 v27, v2
	v_mov_b32_e32 v28, v2
	v_mov_b32_e32 v29, v2
	v_mov_b32_e32 v30, v2
	v_mov_b32_e32 v31, v2
	v_mov_b32_e32 v32, v2
	v_mov_b32_e32 v33, v2
	v_mov_b32_e32 v50, v2
	v_mov_b32_e32 v51, v2
	v_mov_b32_e32 v52, v2
	v_mov_b32_e32 v53, v2
	v_mov_b32_e32 v54, v2
	v_mov_b32_e32 v55, v2
	v_mov_b32_e32 v56, v2
	v_mov_b32_e32 v57, v2
	v_mov_b32_e32 v74, v2
	v_mov_b32_e32 v75, v2
	v_mov_b32_e32 v76, v2
	v_mov_b32_e32 v77, v2
	v_mov_b32_e32 v78, v2
	v_mov_b32_e32 v79, v2
	v_mov_b32_e32 v80, v2
	v_mov_b32_e32 v81, v2
	v_mov_b32_e32 v82, v2
	v_mov_b32_e32 v83, v2
	v_mov_b32_e32 v84, v2
	v_mov_b32_e32 v85, v2
	v_mov_b32_e32 v86, v2
	v_mov_b32_e32 v87, v2
	v_mov_b32_e32 v88, v2
	v_mov_b32_e32 v89, v2
	v_mov_b32_e32 v98, v2
	v_mov_b32_e32 v99, v2
	v_mov_b32_e32 v100, v2
	v_mov_b32_e32 v101, v2
	v_mov_b32_e32 v102, v2
	v_mov_b32_e32 v103, v2
	v_mov_b32_e32 v104, v2
	v_mov_b32_e32 v105, v2
	v_mov_b32_e32 v114, v2
	v_mov_b32_e32 v115, v2
	v_mov_b32_e32 v116, v2
	v_mov_b32_e32 v117, v2
	v_mov_b32_e32 v118, v2
	v_mov_b32_e32 v119, v2
	v_mov_b32_e32 v120, v2
	v_mov_b32_e32 v121, v2
	v_mov_b32_e32 v130, v2
	v_mov_b32_e32 v131, v2
	v_mov_b32_e32 v132, v2
	v_mov_b32_e32 v133, v2
	v_mov_b32_e32 v134, v2
	v_mov_b32_e32 v135, v2
	v_mov_b32_e32 v136, v2
	v_mov_b32_e32 v137, v2
	v_mov_b32_e32 v90, v2
	v_mov_b32_e32 v91, v2
	v_mov_b32_e32 v92, v2
	v_mov_b32_e32 v93, v2
	v_mov_b32_e32 v94, v2
	v_mov_b32_e32 v95, v2
	v_mov_b32_e32 v96, v2
	v_mov_b32_e32 v97, v2
	v_mov_b32_e32 v106, v2
	v_mov_b32_e32 v107, v2
	v_mov_b32_e32 v108, v2
	v_mov_b32_e32 v109, v2
	v_mov_b32_e32 v110, v2
	v_mov_b32_e32 v111, v2
	v_mov_b32_e32 v112, v2
	v_mov_b32_e32 v113, v2
	v_mov_b32_e32 v122, v2
	v_mov_b32_e32 v123, v2
	v_mov_b32_e32 v124, v2
	v_mov_b32_e32 v125, v2
	v_mov_b32_e32 v126, v2
	v_mov_b32_e32 v127, v2
	v_mov_b32_e32 v128, v2
	v_mov_b32_e32 v129, v2
	v_mov_b32_e32 v138, v2
	v_mov_b32_e32 v139, v2
	v_mov_b32_e32 v140, v2
	v_mov_b32_e32 v141, v2
	v_mov_b32_e32 v142, v2
	v_mov_b32_e32 v143, v2
	v_mov_b32_e32 v144, v2
	v_mov_b32_e32 v145, v2
.LBB0_1153:
	ds_read_b128 v[42:45], v168
	ds_read_b128 v[46:49], v168 offset:1024
	ds_read_b128 v[66:69], v168 offset:2048
	ds_read_b128 v[70:73], v168 offset:3072
	ds_read_b128 v[162:165], v169
	ds_read_b128 v[172:175], v169 offset:1024
	ds_read_b128 v[176:179], v169 offset:2048
	ds_read_b128 v[180:183], v169 offset:3072
	s_add_u32 s4, s34, 0xfffe0080
	s_addc_u32 s5, s35, -1
	s_cmp_eq_u32 s57, 4
	s_cselect_b32 s37, s23, s5
	s_cselect_b32 s36, s33, s4
	s_cselect_b32 s5, s21, s56
	s_cselect_b32 s4, s54, s55
	v_lshl_add_u64 v[216:217], s[34:35], 0, v[154:155]
	s_add_i32 m0, s29, 0xc000
	ds_read_b128 v[184:187], v170
	ds_read_b128 v[188:191], v170 offset:1024
	ds_read_b128 v[192:195], v170 offset:2048
	ds_read_b128 v[196:199], v170 offset:3072
	ds_read_b128 v[200:203], v170 offset:4096
	ds_read_b128 v[204:207], v170 offset:5120
	ds_read_b128 v[208:211], v170 offset:6144
	ds_read_b128 v[212:215], v170 offset:7168
	global_load_lds_dwordx4 v[216:217], off
	v_lshl_add_u64 v[216:217], s[34:35], 0, v[156:157]
	s_add_i32 m0, s29, 0xe000
	s_nop 0
	global_load_lds_dwordx4 v[216:217], off
	s_waitcnt vmcnt(8)
	s_waitcnt lgkmcnt(0)
	s_barrier
	s_setprio 1
	s_waitcnt lgkmcnt(0)
	global_load_dword v253, v254, s[98:99]
	s_mov_b32 s100, 0x8000
	s_cmp_eq_u32 s57, 0
	s_cselect_b32 s100, 0x18000, s100
	s_add_u32 s98, s98, s100
	s_addc_u32 s99, s99, 0
	v_mfma_f32_16x16x32_bf16 v[142:145], v[42:45], v[184:187], v[142:145]
	v_mfma_f32_16x16x32_bf16 v[138:141], v[66:69], v[184:187], v[138:141]
	v_mfma_f32_16x16x32_bf16 v[126:129], v[42:45], v[192:195], v[126:129]
	v_mfma_f32_16x16x32_bf16 v[122:125], v[66:69], v[192:195], v[122:125]
	v_mfma_f32_16x16x32_bf16 v[110:113], v[42:45], v[200:203], v[110:113]
	v_mfma_f32_16x16x32_bf16 v[106:109], v[66:69], v[200:203], v[106:109]
	v_mfma_f32_16x16x32_bf16 v[94:97], v[42:45], v[208:211], v[94:97]
	v_mfma_f32_16x16x32_bf16 v[90:93], v[66:69], v[208:211], v[90:93]
	v_mfma_f32_16x16x32_bf16 v[142:145], v[46:49], v[188:191], v[142:145]
	v_mfma_f32_16x16x32_bf16 v[138:141], v[70:73], v[188:191], v[138:141]
	v_mfma_f32_16x16x32_bf16 v[126:129], v[46:49], v[196:199], v[126:129]
	v_mfma_f32_16x16x32_bf16 v[122:125], v[70:73], v[196:199], v[122:125]
	v_mfma_f32_16x16x32_bf16 v[110:113], v[46:49], v[204:207], v[110:113]
	v_mfma_f32_16x16x32_bf16 v[106:109], v[70:73], v[204:207], v[106:109]
	v_mfma_f32_16x16x32_bf16 v[94:97], v[46:49], v[212:215], v[94:97]
	v_mfma_f32_16x16x32_bf16 v[90:93], v[70:73], v[212:215], v[90:93]
	s_setprio 0
	s_setprio 1
	v_mfma_f32_16x16x32_bf16 v[134:137], v[162:165], v[184:187], v[134:137]
	v_mfma_f32_16x16x32_bf16 v[130:133], v[176:179], v[184:187], v[130:133]
	v_mfma_f32_16x16x32_bf16 v[118:121], v[162:165], v[192:195], v[118:121]
	v_mfma_f32_16x16x32_bf16 v[114:117], v[176:179], v[192:195], v[114:117]
	v_mfma_f32_16x16x32_bf16 v[102:105], v[162:165], v[200:203], v[102:105]
	v_mfma_f32_16x16x32_bf16 v[98:101], v[176:179], v[200:203], v[98:101]
	v_mfma_f32_16x16x32_bf16 v[86:89], v[162:165], v[208:211], v[86:89]
	v_mfma_f32_16x16x32_bf16 v[82:85], v[176:179], v[208:211], v[82:85]
	v_mfma_f32_16x16x32_bf16 v[134:137], v[172:175], v[188:191], v[134:137]
	v_mfma_f32_16x16x32_bf16 v[130:133], v[180:183], v[188:191], v[130:133]
	v_mfma_f32_16x16x32_bf16 v[118:121], v[172:175], v[196:199], v[118:121]
	v_mfma_f32_16x16x32_bf16 v[114:117], v[180:183], v[196:199], v[114:117]
	v_mfma_f32_16x16x32_bf16 v[102:105], v[172:175], v[204:207], v[102:105]
	v_mfma_f32_16x16x32_bf16 v[98:101], v[180:183], v[204:207], v[98:101]
	v_mfma_f32_16x16x32_bf16 v[86:89], v[172:175], v[212:215], v[86:89]
	v_mfma_f32_16x16x32_bf16 v[82:85], v[180:183], v[212:215], v[82:85]
	s_setprio 0
	s_barrier
	s_add_i32 s58, s52, s2
	v_lshl_add_u64 v[216:217], s[4:5], 0, v[148:149]
	s_mov_b32 m0, s58
	ds_read_b128 v[184:187], v170 offset:16384
	ds_read_b128 v[188:191], v170 offset:17408
	ds_read_b128 v[192:195], v170 offset:18432
	ds_read_b128 v[196:199], v170 offset:19456
	ds_read_b128 v[200:203], v170 offset:20480
	ds_read_b128 v[204:207], v170 offset:21504
	ds_read_b128 v[208:211], v170 offset:22528
	ds_read_b128 v[212:215], v170 offset:23552
	global_load_lds_dwordx4 v[216:217], off
	s_add_i32 m0, s58, 0x2000
	s_add_u32 s58, s4, 0x20000
	v_lshl_add_u64 v[218:219], s[4:5], 0, v[152:153]
	s_addc_u32 s59, s5, 0
	s_add_i32 s60, s53, s2
	global_load_lds_dwordx4 v[218:219], off
	v_lshl_add_u64 v[220:221], s[58:59], 0, v[148:149]
	s_mov_b32 m0, s60
	v_lshl_add_u64 v[222:223], s[36:37], 0, v[150:151]
	global_load_lds_dwordx4 v[220:221], off
	v_lshl_add_u64 v[220:221], s[58:59], 0, v[152:153]
	s_add_i32 m0, s60, 0x2000
	s_nop 0
	global_load_lds_dwordx4 v[220:221], off
	v_lshl_add_u64 v[220:221], s[36:37], 0, v[146:147]
	s_mov_b32 m0, s29
	s_nop 0
	global_load_lds_dwordx4 v[220:221], off
	s_mov_b32 m0, s31
	s_nop 0
	global_load_lds_dwordx4 v[222:223], off
	s_waitcnt vmcnt(9)
	s_waitcnt lgkmcnt(0)
	s_barrier
	s_setprio 1
	s_waitcnt lgkmcnt(0)
	v_mfma_f32_16x16x32_bf16 v[78:81], v[42:45], v[184:187], v[78:81]
	v_mfma_f32_16x16x32_bf16 v[74:77], v[66:69], v[184:187], v[74:77]
	v_mfma_f32_16x16x32_bf16 v[54:57], v[42:45], v[192:195], v[54:57]
	v_mfma_f32_16x16x32_bf16 v[50:53], v[66:69], v[192:195], v[50:53]
	v_mfma_f32_16x16x32_bf16 v[30:33], v[42:45], v[200:203], v[30:33]
	v_mfma_f32_16x16x32_bf16 v[26:29], v[66:69], v[200:203], v[26:29]
	v_mfma_f32_16x16x32_bf16 v[14:17], v[42:45], v[208:211], v[14:17]
	v_mfma_f32_16x16x32_bf16 v[10:13], v[66:69], v[208:211], v[10:13]
	v_mfma_f32_16x16x32_bf16 v[78:81], v[46:49], v[188:191], v[78:81]
	v_mfma_f32_16x16x32_bf16 v[74:77], v[70:73], v[188:191], v[74:77]
	v_mfma_f32_16x16x32_bf16 v[54:57], v[46:49], v[196:199], v[54:57]
	v_mfma_f32_16x16x32_bf16 v[50:53], v[70:73], v[196:199], v[50:53]
	v_mfma_f32_16x16x32_bf16 v[30:33], v[46:49], v[204:207], v[30:33]
	v_mfma_f32_16x16x32_bf16 v[26:29], v[70:73], v[204:207], v[26:29]
	v_mfma_f32_16x16x32_bf16 v[14:17], v[46:49], v[212:215], v[14:17]
	v_mfma_f32_16x16x32_bf16 v[10:13], v[70:73], v[212:215], v[10:13]
	s_setprio 0
	s_setprio 1
	v_mfma_f32_16x16x32_bf16 v[38:41], v[162:165], v[192:195], v[38:41]
	v_mfma_f32_16x16x32_bf16 v[34:37], v[176:179], v[192:195], v[34:37]
	v_mfma_f32_16x16x32_bf16 v[22:25], v[162:165], v[200:203], v[22:25]
	v_mfma_f32_16x16x32_bf16 v[18:21], v[176:179], v[200:203], v[18:21]
	v_mfma_f32_16x16x32_bf16 v[6:9], v[162:165], v[208:211], v[6:9]
	v_mfma_f32_16x16x32_bf16 v[2:5], v[176:179], v[208:211], v[2:5]
	v_mfma_f32_16x16x32_bf16 v[42:45], v[162:165], v[184:187], v[62:65]
	v_mfma_f32_16x16x32_bf16 v[46:49], v[176:179], v[184:187], v[58:61]
	v_mfma_f32_16x16x32_bf16 v[38:41], v[172:175], v[196:199], v[38:41]
	v_mfma_f32_16x16x32_bf16 v[34:37], v[180:183], v[196:199], v[34:37]
	v_mfma_f32_16x16x32_bf16 v[22:25], v[172:175], v[204:207], v[22:25]
	v_mfma_f32_16x16x32_bf16 v[18:21], v[180:183], v[204:207], v[18:21]
	v_mfma_f32_16x16x32_bf16 v[6:9], v[172:175], v[212:215], v[6:9]
	v_mfma_f32_16x16x32_bf16 v[2:5], v[180:183], v[212:215], v[2:5]
	v_mfma_f32_16x16x32_bf16 v[42:45], v[172:175], v[188:191], v[42:45]
	v_mfma_f32_16x16x32_bf16 v[46:49], v[180:183], v[188:191], v[46:49]
	s_setprio 0
	s_barrier
	s_add_i32 s58, 0, 0x18000
	v_add_u32_e32 v70, s58, v166
	v_add_u32_e32 v171, s92, v166
	ds_read_b128 v[58:61], v70
	ds_read_b128 v[62:65], v70 offset:1024
	ds_read_b128 v[66:69], v70 offset:2048
	ds_read_b128 v[70:73], v70 offset:3072
	ds_read_b128 v[162:165], v171
	ds_read_b128 v[172:175], v171 offset:1024
	ds_read_b128 v[176:179], v171 offset:2048
	ds_read_b128 v[180:183], v171 offset:3072
	s_add_u32 s36, s36, 0x20000
	s_addc_u32 s37, s37, 0
	s_mov_b32 m0, s38
	v_lshl_add_u64 v[224:225], s[36:37], 0, v[146:147]
	ds_read_b128 v[184:187], v170 offset:32768
	ds_read_b128 v[188:191], v170 offset:33792
	ds_read_b128 v[192:195], v170 offset:34816
	ds_read_b128 v[196:199], v170 offset:35840
	ds_read_b128 v[200:203], v170 offset:36864
	ds_read_b128 v[204:207], v170 offset:37888
	ds_read_b128 v[208:211], v170 offset:38912
	ds_read_b128 v[212:215], v170 offset:39936
	global_load_lds_dwordx4 v[224:225], off
	v_lshl_add_u64 v[224:225], s[36:37], 0, v[150:151]
	s_mov_b32 m0, s39
	s_nop 0
	global_load_lds_dwordx4 v[224:225], off
	s_waitcnt vmcnt(9)
	s_waitcnt lgkmcnt(0)
	s_barrier
	s_setprio 1
	s_waitcnt lgkmcnt(0)
	v_mfma_f32_16x16x32_bf16 v[142:145], v[58:61], v[184:187], v[142:145]
	v_mfma_f32_16x16x32_bf16 v[138:141], v[66:69], v[184:187], v[138:141]
	v_mfma_f32_16x16x32_bf16 v[126:129], v[58:61], v[192:195], v[126:129]
	v_mfma_f32_16x16x32_bf16 v[122:125], v[66:69], v[192:195], v[122:125]
	v_mfma_f32_16x16x32_bf16 v[110:113], v[58:61], v[200:203], v[110:113]
	v_mfma_f32_16x16x32_bf16 v[106:109], v[66:69], v[200:203], v[106:109]
	v_mfma_f32_16x16x32_bf16 v[94:97], v[58:61], v[208:211], v[94:97]
	v_mfma_f32_16x16x32_bf16 v[90:93], v[66:69], v[208:211], v[90:93]
	v_mfma_f32_16x16x32_bf16 v[142:145], v[62:65], v[188:191], v[142:145]
	v_mfma_f32_16x16x32_bf16 v[138:141], v[70:73], v[188:191], v[138:141]
	v_mfma_f32_16x16x32_bf16 v[126:129], v[62:65], v[196:199], v[126:129]
	v_mfma_f32_16x16x32_bf16 v[122:125], v[70:73], v[196:199], v[122:125]
	v_mfma_f32_16x16x32_bf16 v[110:113], v[62:65], v[204:207], v[110:113]
	v_mfma_f32_16x16x32_bf16 v[106:109], v[70:73], v[204:207], v[106:109]
	v_mfma_f32_16x16x32_bf16 v[94:97], v[62:65], v[212:215], v[94:97]
	v_mfma_f32_16x16x32_bf16 v[90:93], v[70:73], v[212:215], v[90:93]
	s_setprio 0
	s_setprio 1
	v_mfma_f32_16x16x32_bf16 v[134:137], v[162:165], v[184:187], v[134:137]
	v_mfma_f32_16x16x32_bf16 v[130:133], v[176:179], v[184:187], v[130:133]
	v_mfma_f32_16x16x32_bf16 v[118:121], v[162:165], v[192:195], v[118:121]
	v_mfma_f32_16x16x32_bf16 v[114:117], v[176:179], v[192:195], v[114:117]
	v_mfma_f32_16x16x32_bf16 v[102:105], v[162:165], v[200:203], v[102:105]
	v_mfma_f32_16x16x32_bf16 v[98:101], v[176:179], v[200:203], v[98:101]
	v_mfma_f32_16x16x32_bf16 v[86:89], v[162:165], v[208:211], v[86:89]
	v_mfma_f32_16x16x32_bf16 v[82:85], v[176:179], v[208:211], v[82:85]
	v_mfma_f32_16x16x32_bf16 v[134:137], v[172:175], v[188:191], v[134:137]
	v_mfma_f32_16x16x32_bf16 v[130:133], v[180:183], v[188:191], v[130:133]
	v_mfma_f32_16x16x32_bf16 v[118:121], v[172:175], v[196:199], v[118:121]
	v_mfma_f32_16x16x32_bf16 v[114:117], v[180:183], v[196:199], v[114:117]
	v_mfma_f32_16x16x32_bf16 v[102:105], v[172:175], v[204:207], v[102:105]
	v_mfma_f32_16x16x32_bf16 v[98:101], v[180:183], v[204:207], v[98:101]
	v_mfma_f32_16x16x32_bf16 v[86:89], v[172:175], v[212:215], v[86:89]
	v_mfma_f32_16x16x32_bf16 v[82:85], v[180:183], v[212:215], v[82:85]
	s_setprio 0
	s_barrier
	s_add_i32 s36, s58, s2
	v_lshl_add_u64 v[216:217], v[216:217], 0, s[16:17]
	s_mov_b32 m0, s36
	ds_read_b128 v[184:187], v170 offset:49152
	ds_read_b128 v[188:191], v170 offset:50176
	ds_read_b128 v[192:195], v170 offset:51200
	ds_read_b128 v[196:199], v170 offset:52224
	ds_read_b128 v[200:203], v170 offset:53248
	ds_read_b128 v[204:207], v170 offset:54272
	ds_read_b128 v[208:211], v170 offset:55296
	ds_read_b128 v[212:215], v170 offset:56320
	global_load_lds_dwordx4 v[216:217], off
	s_add_i32 m0, s36, 0x2000
	s_add_u32 s4, s4, 0x20080
	v_lshl_add_u64 v[216:217], v[218:219], 0, s[16:17]
	s_addc_u32 s5, s5, 0
	s_add_i32 s36, s92, s2
	global_load_lds_dwordx4 v[216:217], off
	v_lshl_add_u64 v[216:217], s[4:5], 0, v[148:149]
	s_mov_b32 m0, s36
	s_nop 0
	global_load_lds_dwordx4 v[216:217], off
	v_lshl_add_u64 v[216:217], s[4:5], 0, v[152:153]
	s_add_i32 m0, s36, 0x2000
	s_nop 0
	global_load_lds_dwordx4 v[216:217], off
	v_lshl_add_u64 v[216:217], v[220:221], 0, s[16:17]
	s_mov_b32 m0, s47
	s_nop 0
	global_load_lds_dwordx4 v[216:217], off
	v_lshl_add_u64 v[216:217], v[222:223], 0, s[16:17]
	s_mov_b32 m0, s48
	s_nop 0
	global_load_lds_dwordx4 v[216:217], off
	s_waitcnt vmcnt(8)
	s_waitcnt lgkmcnt(0)
	s_barrier
	s_setprio 1
	s_waitcnt lgkmcnt(0)
	v_mfma_f32_16x16x32_bf16 v[78:81], v[58:61], v[184:187], v[78:81]
	v_mfma_f32_16x16x32_bf16 v[74:77], v[66:69], v[184:187], v[74:77]
	v_mfma_f32_16x16x32_bf16 v[54:57], v[58:61], v[192:195], v[54:57]
	v_mfma_f32_16x16x32_bf16 v[50:53], v[66:69], v[192:195], v[50:53]
	v_mfma_f32_16x16x32_bf16 v[30:33], v[58:61], v[200:203], v[30:33]
	v_mfma_f32_16x16x32_bf16 v[26:29], v[66:69], v[200:203], v[26:29]
	v_mfma_f32_16x16x32_bf16 v[14:17], v[58:61], v[208:211], v[14:17]
	v_mfma_f32_16x16x32_bf16 v[10:13], v[66:69], v[208:211], v[10:13]
	v_mfma_f32_16x16x32_bf16 v[78:81], v[62:65], v[188:191], v[78:81]
	v_mfma_f32_16x16x32_bf16 v[74:77], v[70:73], v[188:191], v[74:77]
	v_mfma_f32_16x16x32_bf16 v[54:57], v[62:65], v[196:199], v[54:57]
	v_mfma_f32_16x16x32_bf16 v[50:53], v[70:73], v[196:199], v[50:53]
	v_mfma_f32_16x16x32_bf16 v[30:33], v[62:65], v[204:207], v[30:33]
	v_mfma_f32_16x16x32_bf16 v[26:29], v[70:73], v[204:207], v[26:29]
	v_mfma_f32_16x16x32_bf16 v[14:17], v[62:65], v[212:215], v[14:17]
	v_mfma_f32_16x16x32_bf16 v[10:13], v[70:73], v[212:215], v[10:13]
	s_setprio 0
	s_setprio 1
	v_mfma_f32_16x16x32_bf16 v[42:45], v[162:165], v[184:187], v[42:45]
	v_mfma_f32_16x16x32_bf16 v[62:65], v[172:175], v[188:191], v[42:45]
	v_mfma_f32_16x16x32_bf16 v[42:45], v[176:179], v[184:187], v[46:49]
	v_mfma_f32_16x16x32_bf16 v[38:41], v[162:165], v[192:195], v[38:41]
	v_mfma_f32_16x16x32_bf16 v[34:37], v[176:179], v[192:195], v[34:37]
	v_mfma_f32_16x16x32_bf16 v[22:25], v[162:165], v[200:203], v[22:25]
	v_mfma_f32_16x16x32_bf16 v[18:21], v[176:179], v[200:203], v[18:21]
	v_mfma_f32_16x16x32_bf16 v[6:9], v[162:165], v[208:211], v[6:9]
	v_mfma_f32_16x16x32_bf16 v[2:5], v[176:179], v[208:211], v[2:5]
	v_mfma_f32_16x16x32_bf16 v[58:61], v[180:183], v[188:191], v[42:45]
	v_mfma_f32_16x16x32_bf16 v[38:41], v[172:175], v[196:199], v[38:41]
	v_mfma_f32_16x16x32_bf16 v[34:37], v[180:183], v[196:199], v[34:37]
	v_mfma_f32_16x16x32_bf16 v[22:25], v[172:175], v[204:207], v[22:25]
	v_mfma_f32_16x16x32_bf16 v[18:21], v[180:183], v[204:207], v[18:21]
	v_mfma_f32_16x16x32_bf16 v[6:9], v[172:175], v[212:215], v[6:9]
	v_mfma_f32_16x16x32_bf16 v[2:5], v[180:183], v[212:215], v[2:5]
	s_setprio 0
	s_barrier
	s_add_i32 s57, s57, 2
	s_add_u32 s34, s34, 0x100
	s_addc_u32 s35, s35, 0
	s_add_u32 s55, s55, 0x100
	s_addc_u32 s56, s56, 0
	s_cmp_gt_u32 s57, 5
	s_cbranch_scc0 .LBB0_1153
	s_and_b64 vcc, exec, s[18:19]
	s_cbranch_vccz .LBB0_1156
	s_barrier

.LBB0_1168:
	v_lshl_add_u64 v[34:35], v[20:21], 0, v[14:15]
	v_add_co_u32_e32 v26, vcc, 0x8200000, v34
	v_lshl_add_u64 v[42:43], v[18:19], 0, v[14:15]
	s_nop 0
	v_addc_co_u32_e32 v27, vcc, 0, v35, vcc
	v_add_co_u32_e32 v30, vcc, 0xa200000, v42
	global_load_dwordx4 v[22:25], v[26:27], off
	s_nop 0
	global_load_dwordx4 v[26:29], v[26:27], off offset:256
	v_addc_co_u32_e32 v31, vcc, 0, v43, vcc
	v_add_co_u32_e32 v38, vcc, 0x9200000, v34
	global_load_dwordx4 v[30:33], v[30:31], off
	s_nop 0
	v_addc_co_u32_e32 v39, vcc, 0, v35, vcc
	global_load_dwordx4 v[34:37], v[38:39], off
	s_nop 0
	global_load_dwordx4 v[38:41], v[38:39], off offset:256
	v_add_co_u32_e32 v42, vcc, 0xaa00000, v42
	v_lshl_add_u64 v[46:47], v[16:17], 0, v[14:15]
	s_nop 0
	v_addc_co_u32_e32 v43, vcc, 0, v43, vcc
	global_load_dwordx4 v[42:45], v[42:43], off
	v_add_co_u32_e64 v48, s[0:1], s17, v46
	v_add_co_u32_e32 v46, vcc, 0xf600000, v46
	s_nop 0
	v_addc_co_u32_e64 v49, s[0:1], 0, v47, s[0:1]
	v_addc_co_u32_e32 v47, vcc, 0, v47, vcc
	s_add_i32 s20, s20, s14
	v_lshl_add_u64 v[16:17], v[16:17], 0, s[4:5]
	v_lshl_add_u64 v[18:19], v[18:19], 0, s[18:19]
	v_lshl_add_u64 v[20:21], v[20:21], 0, s[4:5]
	v_lshl_add_u64 v[254:255], v[20:21], 0, v[14:15]
	v_add_co_u32_e32 v254, vcc, 0x8200000, v254
	s_nop 1
	v_addc_co_u32_e32 v255, vcc, 0, v255, vcc
	global_load_dword v253, v[254:255], off
	global_load_dword v253, v[254:255], off offset:256
	v_add_co_u32_e32 v254, vcc, 0x1000000, v254
	s_nop 1
	v_addc_co_u32_e32 v255, vcc, 0, v255, vcc
	global_load_dword v253, v[254:255], off
	global_load_dword v253, v[254:255], off offset:256
	v_lshl_add_u64 v[254:255], v[18:19], 0, v[14:15]
	v_add_co_u32_e32 v254, vcc, 0xa200000, v254
	s_nop 1
	v_addc_co_u32_e32 v255, vcc, 0, v255, vcc
	global_load_dword v253, v[254:255], off
	v_add_co_u32_e32 v254, vcc, 0x800000, v254
	s_nop 1
	v_addc_co_u32_e32 v255, vcc, 0, v255, vcc
	global_load_dword v253, v[254:255], off
	s_cmpk_gt_i32 s20, 0x1fff
	s_waitcnt vmcnt(11)
	v_lshlrev_b32_e32 v13, 16, v22
	s_waitcnt vmcnt(10)
	v_lshlrev_b32_e32 v54, 16, v26
	v_and_b32_e32 v55, 0xffff0000, v22
	v_and_b32_e32 v56, 0xffff0000, v26
	v_and_b32_e32 v22, 0xffff0000, v23
	v_lshlrev_b32_e32 v23, 16, v23
	v_and_b32_e32 v26, 0xffff0000, v27
	v_lshlrev_b32_e32 v27, 16, v27
	v_fma_f32 v13, -v10, v54, v13
	v_fma_f32 v54, -v10, v56, v55
	v_and_b32_e32 v50, 0xffff0000, v24
	v_lshlrev_b32_e32 v51, 16, v24
	v_and_b32_e32 v52, 0xffff0000, v28
	v_lshlrev_b32_e32 v53, 16, v28
	v_and_b32_e32 v24, 0xffff0000, v25
	v_lshlrev_b32_e32 v25, 16, v25
	v_and_b32_e32 v28, 0xffff0000, v29
	v_lshlrev_b32_e32 v29, 16, v29
	v_pk_fma_f32 v[22:23], v[10:11], v[26:27], v[22:23] neg_lo:[1,0,0] neg_hi:[1,0,0]
	v_mul_f32_e32 v63, v54, v54
	s_waitcnt vmcnt(8)
	v_lshlrev_b32_e32 v64, 16, v34
	s_waitcnt vmcnt(7)
	v_lshlrev_b32_e32 v65, 16, v38
	v_and_b32_e32 v66, 0xffff0000, v34
	v_and_b32_e32 v67, 0xffff0000, v38
	v_pk_fma_f32 v[24:25], v[10:11], v[28:29], v[24:25] neg_lo:[1,0,0] neg_hi:[1,0,0]
	v_pk_mul_f32 v[28:29], v[22:23], v[22:23]
	v_and_b32_e32 v34, 0xffff0000, v35
	v_lshlrev_b32_e32 v35, 16, v35
	v_and_b32_e32 v38, 0xffff0000, v39
	v_lshlrev_b32_e32 v39, 16, v39
	v_fmac_f32_e32 v63, v13, v13
	v_fma_f32 v64, -v10, v65, v64
	v_fma_f32 v65, -v10, v67, v66
	v_pk_fma_f32 v[26:27], v[10:11], v[52:53], v[50:51] neg_lo:[1,0,0] neg_hi:[1,0,0]
	v_and_b32_e32 v50, 0xffff0000, v36
	v_lshlrev_b32_e32 v51, 16, v36
	v_and_b32_e32 v52, 0xffff0000, v40
	v_lshlrev_b32_e32 v53, 16, v40
	v_and_b32_e32 v36, 0xffff0000, v37
	v_lshlrev_b32_e32 v37, 16, v37
	v_and_b32_e32 v40, 0xffff0000, v41
	v_lshlrev_b32_e32 v41, 16, v41
	v_pk_fma_f32 v[34:35], v[10:11], v[38:39], v[34:35] neg_lo:[1,0,0] neg_hi:[1,0,0]
	v_add_f32_e32 v29, v29, v63
	v_mul_f32_e32 v63, v65, v65
	v_lshlrev_b32_e32 v55, 16, v30
	v_and_b32_e32 v56, 0xffff0000, v30
	v_lshlrev_b32_e32 v57, 16, v31
	v_and_b32_e32 v58, 0xffff0000, v31
	v_pk_mul_f32 v[30:31], v[26:27], v[26:27]
	v_pk_fma_f32 v[36:37], v[10:11], v[40:41], v[36:37] neg_lo:[1,0,0] neg_hi:[1,0,0]
	v_pk_mul_f32 v[40:41], v[34:35], v[34:35]
	v_add_f32_e32 v28, v28, v29
	v_fmac_f32_e32 v63, v64, v64
	v_pk_fma_f32 v[38:39], v[10:11], v[52:53], v[50:51] neg_lo:[1,0,0] neg_hi:[1,0,0]
	v_add_f32_e32 v28, v31, v28
	v_add_f32_e32 v29, v41, v63
	v_lshlrev_b32_e32 v59, 16, v32
	v_and_b32_e32 v60, 0xffff0000, v32
	v_lshlrev_b32_e32 v61, 16, v33
	v_and_b32_e32 v62, 0xffff0000, v33
	v_pk_mul_f32 v[32:33], v[24:25], v[24:25]
	s_waitcnt vmcnt(6)
	v_lshlrev_b32_e32 v50, 16, v42
	v_and_b32_e32 v51, 0xffff0000, v42
	v_lshlrev_b32_e32 v52, 16, v43
	v_and_b32_e32 v53, 0xffff0000, v43
	v_pk_mul_f32 v[42:43], v[38:39], v[38:39]
	v_add_f32_e32 v28, v30, v28
	v_add_f32_e32 v29, v40, v29
	v_add_f32_e32 v28, v33, v28
	v_add_f32_e32 v29, v43, v29
	v_lshlrev_b32_e32 v66, 16, v44
	v_and_b32_e32 v67, 0xffff0000, v44
	v_lshlrev_b32_e32 v68, 16, v45
	v_and_b32_e32 v69, 0xffff0000, v45
	v_pk_mul_f32 v[44:45], v[36:37], v[36:37]
	v_add_f32_e32 v28, v32, v28
	v_add_f32_e32 v29, v42, v29
	v_add_f32_e32 v29, v45, v29
	v_add_f32_dpp v28, v28, v28 quad_perm:[1,0,3,2] row_mask:0xf bank_mask:0xf bound_ctrl:1
	v_add_f32_e32 v29, v44, v29
	s_nop 0
	v_add_f32_dpp v28, v28, v28 quad_perm:[2,3,0,1] row_mask:0xf bank_mask:0xf bound_ctrl:1
	v_add_f32_dpp v29, v29, v29 quad_perm:[1,0,3,2] row_mask:0xf bank_mask:0xf bound_ctrl:1
	s_nop 0
	v_add_f32_dpp v28, v28, v28 row_half_mirror row_mask:0xf bank_mask:0xf bound_ctrl:1
	v_add_f32_dpp v29, v29, v29 quad_perm:[2,3,0,1] row_mask:0xf bank_mask:0xf bound_ctrl:1
	s_nop 0
	v_add_f32_dpp v28, v28, v28 row_ror:8 row_mask:0xf bank_mask:0xf bound_ctrl:1
	v_fmamk_f32 v28, v28, 0x3c000000, v1
	v_add_f32_dpp v29, v29, v29 row_half_mirror row_mask:0xf bank_mask:0xf bound_ctrl:1
	v_mul_f32_e32 v30, 0x4b800000, v28
	v_cmp_gt_f32_e32 vcc, s15, v28
	v_add_f32_dpp v29, v29, v29 row_ror:8 row_mask:0xf bank_mask:0xf bound_ctrl:1
	v_fmamk_f32 v29, v29, 0x3c000000, v1
	v_cndmask_b32_e32 v28, v28, v30, vcc
	v_rsq_f32_e32 v28, v28
	v_mul_f32_e32 v30, 0x4b800000, v29
	v_cmp_gt_f32_e64 s[0:1], s15, v29
	s_nop 1
	v_cndmask_b32_e64 v29, v29, v30, s[0:1]
	v_rsq_f32_e32 v29, v29
	v_mul_f32_e32 v30, 0x45800000, v28
	v_cndmask_b32_e32 v28, v28, v30, vcc
	v_mul_f32_e32 v28, 0x3f4ccccd, v28
	v_mul_f32_e32 v30, 0x45800000, v29
	v_mul_f32_e32 v13, v13, v28
	v_mul_f32_e32 v31, v54, v28
	v_mul_f32_e32 v23, v23, v28
	v_mul_f32_e32 v22, v22, v28
	v_mul_f32_e32 v27, v27, v28
	v_mul_f32_e32 v26, v26, v28
	v_mul_f32_e32 v25, v25, v28
	v_mul_f32_e32 v24, v24, v28
	v_cndmask_b32_e64 v28, v29, v30, s[0:1]
	v_mul_f32_e32 v29, v3, v31
	v_mul_f32_e32 v23, v4, v23
	v_mul_f32_e32 v22, v5, v22
	v_mul_f32_e32 v27, v6, v27
	v_mul_f32_e32 v26, v7, v26
	v_mul_f32_e32 v25, v8, v25
	v_mul_f32_e32 v28, 0x3f4ccccd, v28
	v_mul_f32_e32 v13, v2, v13
	v_mul_f32_e32 v24, v9, v24
	v_mul_f32_e32 v29, v29, v56
	v_mul_f32_e32 v23, v23, v57
	v_mul_f32_e32 v30, v22, v58
	v_mul_f32_e32 v27, v27, v59
	v_mul_f32_e32 v26, v26, v60
	v_mul_f32_e32 v25, v25, v61
	v_mul_f32_e32 v33, v65, v28
	v_mul_f32_e32 v35, v35, v28
	v_mul_f32_e32 v34, v34, v28
	v_mul_f32_e32 v39, v39, v28
	v_mul_f32_e32 v13, v13, v55
	v_mul_f32_e32 v31, v24, v62
	v_mul_f32_e32 v32, v64, v28
	v_mul_f32_e32 v38, v38, v28
	v_mul_f32_e32 v37, v37, v28
	v_mul_f32_e32 v28, v36, v28
	v_cvt_pk_bf16_f32 v22, v13, v29
	v_cvt_pk_bf16_f32 v23, v23, v30
	v_cvt_pk_bf16_f32 v24, v27, v26
	v_cvt_pk_bf16_f32 v25, v25, v31
	v_mul_f32_e32 v26, v3, v33
	v_mul_f32_e32 v27, v4, v35
	v_mul_f32_e32 v29, v5, v34
	v_mul_f32_e32 v30, v6, v39
	v_mul_f32_e32 v13, v2, v32
	v_mul_f32_e32 v31, v7, v38
	v_mul_f32_e32 v32, v8, v37
	v_mul_f32_e32 v28, v9, v28
	global_store_dwordx4 v[48:49], v[22:25], off
	v_mul_f32_e32 v13, v13, v50
	v_mul_f32_e32 v28, v28, v69
	v_mul_f32_e32 v22, v26, v51
	v_mul_f32_e32 v23, v27, v52
	v_mul_f32_e32 v24, v29, v53
	v_mul_f32_e32 v25, v30, v66
	v_mul_f32_e32 v26, v31, v67
	v_mul_f32_e32 v27, v32, v68
	v_cvt_pk_bf16_f32 v22, v13, v22
	v_cvt_pk_bf16_f32 v23, v23, v24
	v_cvt_pk_bf16_f32 v24, v25, v26
	v_cvt_pk_bf16_f32 v25, v27, v28
	global_store_dwordx4 v[46:47], v[22:25], off
	s_cbranch_scc0 .LBB0_1168
